# grid barrier: release on the cross-XCD arrival counter itself (poll TOP >= (gen+1)*nx), no separate generation-word hop
# speedup vs baseline: 1.0039x; 1.0039x over previous
; __device__ __forceinline__ unsigned xb_ld(unsigned* p)              { return __hip_atomic_load(p, __ATOMIC_RELAXED, __HIP_MEMORY_SCOPE_AGENT); }
; __device__ __forceinline__ unsigned xb_add(unsigned* p, unsigned v) { return __hip_atomic_fetch_add(p, v, __ATOMIC_RELAXED, __HIP_MEMORY_SCOPE_AGENT); }
; #define XB_SPIN(cond, bar) do { unsigned _sp = 0; while (cond) { __builtin_amdgcn_s_sleep(1); \
;     if ((++_sp & 255u) == 0u) { if (xb_ld(&(bar)[XB_TMO])) break; if (_sp > XB_SPIN_CAP) { atomicAdd(&(bar)[XB_TMO], 1u); break; } } } } while (0)
; __device__ __forceinline__ void xcd_barrier(const XcdBarrier& b) {
;     ...
;         const unsigned old = xb_add(&bar[XB_XSUB(b.x)], 1u);
;         const unsigned gen = old / nloc;
;         if (old + 1u == (gen + 1u) * nloc) {
;             __builtin_amdgcn_fence(__ATOMIC_RELEASE, "agent");
;             asm volatile("s_waitcnt vmcnt(0)" ::: "memory");
;             const unsigned og = xb_add(&bar[XB_TOP], 1u);
;             const unsigned tg = og / nx;
;             if (og + 1u == (tg + 1u) * nx) xb_add(&bar[XB_TOPGEN], 1u);
;             else XB_SPIN(xb_ld(&bar[XB_TOPGEN]) == tg, bar);
;             __builtin_amdgcn_fence(__ATOMIC_ACQUIRE, "agent");
;             xb_add(&bar[XB_XGEN(b.x)], 1u);
;             asm volatile("s_waitcnt vmcnt(0)" ::: "memory");
;         } else {
;             XB_SPIN(xb_ld(&bar[XB_XGEN(b.x)]) == gen, bar);
.LBB0_307:
	v_readlane_b32 s4, v254, 16
	s_lshl_b32 s4, s4, 8
	v_readlane_b32 s10, v254, 12
	v_readlane_b32 s11, v254, 13
	s_add_u32 s4, s10, s4
	s_addc_u32 s5, s11, 0
	v_mov_b32_e32 v3, 0x1000
	v_mov_b32_e32 v5, 1
	global_atomic_add v5, v3, v5, s[4:5] offset:1024 sc0
	v_cvt_f32_u32_e32 v3, v4
	v_sub_u32_e32 v6, 0, v4
	v_rcp_iflag_f32_e32 v3, v3
	s_nop 0
	v_mul_f32_e32 v3, 0x4f7ffffe, v3
	v_cvt_u32_f32_e32 v3, v3
	v_mul_lo_u32 v6, v6, v3
	v_mul_hi_u32 v6, v3, v6
	v_add_u32_e32 v3, v3, v6
	s_waitcnt vmcnt(0)
	v_mul_hi_u32 v3, v5, v3
	v_mul_lo_u32 v6, v3, v4
	v_sub_u32_e32 v6, v5, v6
	v_add_u32_e32 v7, 1, v3
	v_cmp_ge_u32_e32 vcc, v6, v4
	v_add_u32_e32 v5, 1, v5
	s_nop 0
	v_cndmask_b32_e32 v3, v3, v7, vcc
	v_sub_u32_e32 v7, v6, v4
	v_cndmask_b32_e32 v6, v6, v7, vcc
	v_add_u32_e32 v7, 1, v3
	v_cmp_ge_u32_e32 vcc, v6, v4
	s_nop 1
	v_cndmask_b32_e32 v3, v3, v7, vcc
	v_mul_lo_u32 v6, v4, v3
	v_add_u32_e32 v4, v6, v4
	v_cmp_ne_u32_e32 vcc, v5, v4
	s_and_saveexec_b64 s[10:11], vcc
	s_xor_b64 s[10:11], exec, s[10:11]
	s_cbranch_execz .LBB0_321
	s_waitcnt lgkmcnt(0)
	s_add_u32 s18, s84, 0x33400
	s_addc_u32 s19, s85, 0
	v_add_u32_e32 v3, 1, v3
	v_mul_lo_u32 v3, v3, v2
	v_mov_b32_e32 v2, 0
	global_load_dword v2, v2, s[18:19] sc1
	s_waitcnt vmcnt(0)
	v_cmp_lt_u32_e32 vcc, v2, v3
	s_and_saveexec_b64 s[14:15], vcc
	s_cbranch_execz .LBB0_320
	s_add_u32 s16, s84, 0x30200
	s_addc_u32 s17, s85, 0
	s_mov_b32 s30, 1
	s_mov_b64 s[20:21], 0
	v_mov_b32_e32 v2, 0
	s_branch .LBB0_311

; __device__ __forceinline__ unsigned xb_ld(unsigned* p)              { return __hip_atomic_load(p, __ATOMIC_RELAXED, __HIP_MEMORY_SCOPE_AGENT); }
; #define XB_SPIN(cond, bar) do { unsigned _sp = 0; while (cond) { __builtin_amdgcn_s_sleep(1); \
;     if ((++_sp & 255u) == 0u) { if (xb_ld(&(bar)[XB_TMO])) break; if (_sp > XB_SPIN_CAP) { atomicAdd(&(bar)[XB_TMO], 1u); break; } } } } while (0)
; __device__ __forceinline__ void xcd_barrier(const XcdBarrier& b) {
;     ...
;             else XB_SPIN(xb_ld(&bar[XB_TOPGEN]) == tg, bar);
.LBB0_313:
	global_load_dword v4, v2, s[18:19] sc1
	s_add_i32 s30, s30, 1
	s_mov_b64 s[26:27], -1
	s_waitcnt vmcnt(0)
	v_cmp_ge_u32_e32 vcc, v4, v3
	s_orn2_b64 s[24:25], vcc, exec
	s_branch .LBB0_310

; __device__ __forceinline__ unsigned xb_ld(unsigned* p)              { return __hip_atomic_load(p, __ATOMIC_RELAXED, __HIP_MEMORY_SCOPE_AGENT); }
; __device__ __forceinline__ unsigned xb_add(unsigned* p, unsigned v) { return __hip_atomic_fetch_add(p, v, __ATOMIC_RELAXED, __HIP_MEMORY_SCOPE_AGENT); }
; #define XB_SPIN(cond, bar) do { unsigned _sp = 0; while (cond) { __builtin_amdgcn_s_sleep(1); \
;     if ((++_sp & 255u) == 0u) { if (xb_ld(&(bar)[XB_TMO])) break; if (_sp > XB_SPIN_CAP) { atomicAdd(&(bar)[XB_TMO], 1u); break; } } } } while (0)
; __device__ __forceinline__ void xcd_barrier(const XcdBarrier& b) {
;     ...
;             asm volatile("s_waitcnt vmcnt(0)" ::: "memory");
;             const unsigned og = xb_add(&bar[XB_TOP], 1u);
;             const unsigned tg = og / nx;
;             if (og + 1u == (tg + 1u) * nx) xb_add(&bar[XB_TOPGEN], 1u);
;             else XB_SPIN(xb_ld(&bar[XB_TOPGEN]) == tg, bar);
;             __builtin_amdgcn_fence(__ATOMIC_ACQUIRE, "agent");
.LBB0_324:
	s_or_b64 exec, exec, s[14:15]
	v_cvt_f32_u32_e32 v5, v2
	s_waitcnt vmcnt(0)
	v_readfirstlane_b32 s10, v4
	s_add_u32 s14, s84, 0x33500
	s_addc_u32 s15, s85, 0
	v_rcp_iflag_f32_e32 v5, v5
	v_add_u32_e32 v3, s10, v3
	v_add_u32_e32 v6, 1, v3
	s_mov_b64 s[16:17], 0
	v_mul_f32_e32 v4, 0x4f7ffffe, v5
	v_cvt_u32_f32_e32 v4, v4
	v_sub_u32_e32 v5, 0, v2
	v_mul_lo_u32 v5, v5, v4
	v_mul_hi_u32 v5, v4, v5
	v_add_u32_e32 v4, v4, v5
	v_mul_hi_u32 v4, v3, v4
	v_mul_lo_u32 v5, v4, v2
	v_sub_u32_e32 v3, v3, v5
	v_add_u32_e32 v7, 1, v4
	v_cmp_ge_u32_e32 vcc, v3, v2
	v_sub_u32_e32 v5, v3, v2
	s_nop 0
	v_cndmask_b32_e32 v4, v4, v7, vcc
	v_cndmask_b32_e32 v3, v3, v5, vcc
	v_add_u32_e32 v5, 1, v4
	v_cmp_ge_u32_e32 vcc, v3, v2
	s_nop 1
	v_cndmask_b32_e32 v4, v4, v5, vcc
	v_mul_lo_u32 v3, v2, v4
	v_add_u32_e32 v2, v3, v2
	v_mov_b32_e32 v8, v2
	v_cmp_ne_u32_e32 vcc, v6, v2
	v_mov_b64_e32 v[2:3], s[14:15]
	s_and_saveexec_b64 s[10:11], vcc
	s_cbranch_execz .LBB0_336
	s_add_u32 s100, s84, 0x33400
	s_addc_u32 s101, s85, 0
	v_mov_b32_e32 v2, 0
	global_load_dword v3, v2, s[100:101] sc1
	s_mov_b64 s[20:21], 0
	s_waitcnt vmcnt(0)
	v_cmp_lt_u32_e32 vcc, v3, v8
	s_and_saveexec_b64 s[18:19], vcc
	s_cbranch_execz .LBB0_335
	s_add_u32 s16, s84, 0x30200
	s_addc_u32 s17, s85, 0
	s_mov_b32 s30, 1
	s_branch .LBB0_328

; __device__ __forceinline__ unsigned xb_ld(unsigned* p)              { return __hip_atomic_load(p, __ATOMIC_RELAXED, __HIP_MEMORY_SCOPE_AGENT); }
; #define XB_SPIN(cond, bar) do { unsigned _sp = 0; while (cond) { __builtin_amdgcn_s_sleep(1); \
;     if ((++_sp & 255u) == 0u) { if (xb_ld(&(bar)[XB_TMO])) break; if (_sp > XB_SPIN_CAP) { atomicAdd(&(bar)[XB_TMO], 1u); break; } } } } while (0)
; __device__ __forceinline__ void xcd_barrier(const XcdBarrier& b) {
;     ...
;             else XB_SPIN(xb_ld(&bar[XB_TOPGEN]) == tg, bar);
.LBB0_330:
	global_load_dword v3, v2, s[100:101] sc1
	s_add_i32 s30, s30, 1
	s_mov_b64 s[24:25], -1
	s_waitcnt vmcnt(0)
	v_cmp_ge_u32_e32 vcc, v3, v8
	s_orn2_b64 s[28:29], vcc, exec
	s_branch .LBB0_327

; __device__ __forceinline__ unsigned xb_add(unsigned* p, unsigned v) { return __hip_atomic_fetch_add(p, v, __ATOMIC_RELAXED, __HIP_MEMORY_SCOPE_AGENT); }
; __device__ __forceinline__ void xcd_barrier(const XcdBarrier& b) {
;     ...
;             __builtin_amdgcn_fence(__ATOMIC_ACQUIRE, "agent");
;             xb_add(&bar[XB_XGEN(b.x)], 1u);
;             asm volatile("s_waitcnt vmcnt(0)" ::: "memory");
.LBB0_338:
	s_or_b64 exec, exec, s[10:11]
	v_mov_b32_e32 v2, 0x2000
	v_mov_b32_e32 v3, 1
	s_waitcnt vmcnt(0)
	s_waitcnt vmcnt(0)
	s_branch .LBB0_339

; __device__ __forceinline__ unsigned xb_ld(unsigned* p)              { return __hip_atomic_load(p, __ATOMIC_RELAXED, __HIP_MEMORY_SCOPE_AGENT); }
; __device__ __forceinline__ unsigned xb_add(unsigned* p, unsigned v) { return __hip_atomic_fetch_add(p, v, __ATOMIC_RELAXED, __HIP_MEMORY_SCOPE_AGENT); }
; #define XB_SPIN(cond, bar) do { unsigned _sp = 0; while (cond) { __builtin_amdgcn_s_sleep(1); \
;     if ((++_sp & 255u) == 0u) { if (xb_ld(&(bar)[XB_TMO])) break; if (_sp > XB_SPIN_CAP) { atomicAdd(&(bar)[XB_TMO], 1u); break; } } } } while (0)
; __device__ __forceinline__ void xcd_barrier(const XcdBarrier& b) {
;     ...
;         const unsigned old = xb_add(&bar[XB_XSUB(b.x)], 1u);
;         const unsigned gen = old / nloc;
;         if (old + 1u == (gen + 1u) * nloc) {
;             __builtin_amdgcn_fence(__ATOMIC_RELEASE, "agent");
;             asm volatile("s_waitcnt vmcnt(0)" ::: "memory");
;             const unsigned og = xb_add(&bar[XB_TOP], 1u);
;             const unsigned tg = og / nx;
;             if (og + 1u == (tg + 1u) * nx) xb_add(&bar[XB_TOPGEN], 1u);
;             else XB_SPIN(xb_ld(&bar[XB_TOPGEN]) == tg, bar);
;             __builtin_amdgcn_fence(__ATOMIC_ACQUIRE, "agent");
;             xb_add(&bar[XB_XGEN(b.x)], 1u);
;             asm volatile("s_waitcnt vmcnt(0)" ::: "memory");
;         } else {
;             XB_SPIN(xb_ld(&bar[XB_XGEN(b.x)]) == gen, bar);
.LBB0_538:
	v_readlane_b32 s4, v254, 16
	s_lshl_b32 s4, s4, 8
	v_readlane_b32 s12, v254, 12
	v_readlane_b32 s13, v254, 13
	s_add_u32 s4, s12, s4
	s_addc_u32 s5, s13, 0
	v_mov_b32_e32 v3, 0x1000
	v_mov_b32_e32 v5, 1
	global_atomic_add v5, v3, v5, s[4:5] offset:1024 sc0
	v_cvt_f32_u32_e32 v3, v4
	v_sub_u32_e32 v6, 0, v4
	v_rcp_iflag_f32_e32 v3, v3
	s_nop 0
	v_mul_f32_e32 v3, 0x4f7ffffe, v3
	v_cvt_u32_f32_e32 v3, v3
	v_mul_lo_u32 v6, v6, v3
	v_mul_hi_u32 v6, v3, v6
	v_add_u32_e32 v3, v3, v6
	s_waitcnt vmcnt(0)
	v_mul_hi_u32 v3, v5, v3
	v_mul_lo_u32 v6, v3, v4
	v_sub_u32_e32 v6, v5, v6
	v_add_u32_e32 v7, 1, v3
	v_cmp_ge_u32_e32 vcc, v6, v4
	v_add_u32_e32 v5, 1, v5
	s_nop 0
	v_cndmask_b32_e32 v3, v3, v7, vcc
	v_sub_u32_e32 v7, v6, v4
	v_cndmask_b32_e32 v6, v6, v7, vcc
	v_add_u32_e32 v7, 1, v3
	v_cmp_ge_u32_e32 vcc, v6, v4
	s_nop 1
	v_cndmask_b32_e32 v3, v3, v7, vcc
	v_mul_lo_u32 v6, v4, v3
	v_add_u32_e32 v4, v6, v4
	v_cmp_ne_u32_e32 vcc, v5, v4
	s_and_saveexec_b64 s[12:13], vcc
	s_xor_b64 s[12:13], exec, s[12:13]
	s_cbranch_execz .LBB0_552
	s_waitcnt lgkmcnt(0)
	s_add_u32 s18, s84, 0x33400
	s_addc_u32 s19, s85, 0
	v_add_u32_e32 v3, 1, v3
	v_mul_lo_u32 v3, v3, v2
	v_mov_b32_e32 v2, 0
	global_load_dword v2, v2, s[18:19] sc1
	s_waitcnt vmcnt(0)
	v_cmp_lt_u32_e32 vcc, v2, v3
	s_and_saveexec_b64 s[14:15], vcc
	s_cbranch_execz .LBB0_551
	s_add_u32 s16, s84, 0x30200
	s_addc_u32 s17, s85, 0
	s_mov_b32 s30, 1
	s_mov_b64 s[20:21], 0
	v_mov_b32_e32 v2, 0
	s_branch .LBB0_542

; __device__ __forceinline__ unsigned xb_ld(unsigned* p)              { return __hip_atomic_load(p, __ATOMIC_RELAXED, __HIP_MEMORY_SCOPE_AGENT); }
; __device__ __forceinline__ unsigned xb_add(unsigned* p, unsigned v) { return __hip_atomic_fetch_add(p, v, __ATOMIC_RELAXED, __HIP_MEMORY_SCOPE_AGENT); }
; #define XB_SPIN(cond, bar) do { unsigned _sp = 0; while (cond) { __builtin_amdgcn_s_sleep(1); \
;     if ((++_sp & 255u) == 0u) { if (xb_ld(&(bar)[XB_TMO])) break; if (_sp > XB_SPIN_CAP) { atomicAdd(&(bar)[XB_TMO], 1u); break; } } } } while (0)
; __device__ __forceinline__ void xcd_barrier(const XcdBarrier& b) {
;     ...
;             asm volatile("s_waitcnt vmcnt(0)" ::: "memory");
;             const unsigned og = xb_add(&bar[XB_TOP], 1u);
;             const unsigned tg = og / nx;
;             if (og + 1u == (tg + 1u) * nx) xb_add(&bar[XB_TOPGEN], 1u);
;             else XB_SPIN(xb_ld(&bar[XB_TOPGEN]) == tg, bar);
;             __builtin_amdgcn_fence(__ATOMIC_ACQUIRE, "agent");
.LBB0_555:
	s_or_b64 exec, exec, s[14:15]
	v_cvt_f32_u32_e32 v5, v2
	s_waitcnt vmcnt(0)
	v_readfirstlane_b32 s12, v4
	s_add_u32 s14, s84, 0x33500
	s_addc_u32 s15, s85, 0
	v_rcp_iflag_f32_e32 v5, v5
	v_add_u32_e32 v3, s12, v3
	v_add_u32_e32 v6, 1, v3
	s_mov_b64 s[16:17], 0
	v_mul_f32_e32 v4, 0x4f7ffffe, v5
	v_cvt_u32_f32_e32 v4, v4
	v_sub_u32_e32 v5, 0, v2
	v_mul_lo_u32 v5, v5, v4
	v_mul_hi_u32 v5, v4, v5
	v_add_u32_e32 v4, v4, v5
	v_mul_hi_u32 v4, v3, v4
	v_mul_lo_u32 v5, v4, v2
	v_sub_u32_e32 v3, v3, v5
	v_add_u32_e32 v7, 1, v4
	v_cmp_ge_u32_e32 vcc, v3, v2
	v_sub_u32_e32 v5, v3, v2
	s_nop 0
	v_cndmask_b32_e32 v4, v4, v7, vcc
	v_cndmask_b32_e32 v3, v3, v5, vcc
	v_add_u32_e32 v5, 1, v4
	v_cmp_ge_u32_e32 vcc, v3, v2
	s_nop 1
	v_cndmask_b32_e32 v4, v4, v5, vcc
	v_mul_lo_u32 v3, v2, v4
	v_add_u32_e32 v2, v3, v2
	v_mov_b32_e32 v8, v2
	v_cmp_ne_u32_e32 vcc, v6, v2
	v_mov_b64_e32 v[2:3], s[14:15]
	s_and_saveexec_b64 s[12:13], vcc
	s_cbranch_execz .LBB0_567
	s_add_u32 s100, s84, 0x33400
	s_addc_u32 s101, s85, 0
	v_mov_b32_e32 v2, 0
	global_load_dword v3, v2, s[100:101] sc1
	s_mov_b64 s[20:21], 0
	s_waitcnt vmcnt(0)
	v_cmp_lt_u32_e32 vcc, v3, v8
	s_and_saveexec_b64 s[18:19], vcc
	s_cbranch_execz .LBB0_566
	s_add_u32 s16, s84, 0x30200
	s_addc_u32 s17, s85, 0
	s_mov_b32 s30, 1
	s_branch .LBB0_559

; __device__ __forceinline__ unsigned xb_add(unsigned* p, unsigned v) { return __hip_atomic_fetch_add(p, v, __ATOMIC_RELAXED, __HIP_MEMORY_SCOPE_AGENT); }
; __device__ __forceinline__ void xcd_barrier(const XcdBarrier& b) {
;     ...
;             __builtin_amdgcn_fence(__ATOMIC_ACQUIRE, "agent");
;             xb_add(&bar[XB_XGEN(b.x)], 1u);
;             asm volatile("s_waitcnt vmcnt(0)" ::: "memory");
.LBB0_569:
	s_or_b64 exec, exec, s[12:13]
	v_mov_b32_e32 v2, 0x2000
	v_mov_b32_e32 v3, 1
	s_waitcnt vmcnt(0)
	s_waitcnt vmcnt(0)
	s_branch .LBB0_570

; __device__ __forceinline__ unsigned xb_ld(unsigned* p)              { return __hip_atomic_load(p, __ATOMIC_RELAXED, __HIP_MEMORY_SCOPE_AGENT); }
; __device__ __forceinline__ unsigned xb_add(unsigned* p, unsigned v) { return __hip_atomic_fetch_add(p, v, __ATOMIC_RELAXED, __HIP_MEMORY_SCOPE_AGENT); }
; #define XB_SPIN(cond, bar) do { unsigned _sp = 0; while (cond) { __builtin_amdgcn_s_sleep(1); \
;     if ((++_sp & 255u) == 0u) { if (xb_ld(&(bar)[XB_TMO])) break; if (_sp > XB_SPIN_CAP) { atomicAdd(&(bar)[XB_TMO], 1u); break; } } } } while (0)
; __device__ __forceinline__ void xcd_barrier(const XcdBarrier& b) {
;     ...
;         const unsigned old = xb_add(&bar[XB_XSUB(b.x)], 1u);
;         const unsigned gen = old / nloc;
;         if (old + 1u == (gen + 1u) * nloc) {
;             __builtin_amdgcn_fence(__ATOMIC_RELEASE, "agent");
;             asm volatile("s_waitcnt vmcnt(0)" ::: "memory");
;             const unsigned og = xb_add(&bar[XB_TOP], 1u);
;             const unsigned tg = og / nx;
;             if (og + 1u == (tg + 1u) * nx) xb_add(&bar[XB_TOPGEN], 1u);
;             else XB_SPIN(xb_ld(&bar[XB_TOPGEN]) == tg, bar);
;             __builtin_amdgcn_fence(__ATOMIC_ACQUIRE, "agent");
;             xb_add(&bar[XB_XGEN(b.x)], 1u);
;             asm volatile("s_waitcnt vmcnt(0)" ::: "memory");
;         } else {
;             XB_SPIN(xb_ld(&bar[XB_XGEN(b.x)]) == gen, bar);
.LBB0_649:
	v_readlane_b32 s4, v254, 16
	s_lshl_b32 s4, s4, 8
	v_readlane_b32 s12, v254, 12
	v_readlane_b32 s13, v254, 13
	s_add_u32 s4, s12, s4
	s_addc_u32 s5, s13, 0
	v_mov_b32_e32 v3, 0x1000
	v_mov_b32_e32 v5, 1
	global_atomic_add v5, v3, v5, s[4:5] offset:1024 sc0
	v_cvt_f32_u32_e32 v3, v4
	v_sub_u32_e32 v6, 0, v4
	v_rcp_iflag_f32_e32 v3, v3
	s_nop 0
	v_mul_f32_e32 v3, 0x4f7ffffe, v3
	v_cvt_u32_f32_e32 v3, v3
	v_mul_lo_u32 v6, v6, v3
	v_mul_hi_u32 v6, v3, v6
	v_add_u32_e32 v3, v3, v6
	s_waitcnt vmcnt(0)
	v_mul_hi_u32 v3, v5, v3
	v_mul_lo_u32 v6, v3, v4
	v_sub_u32_e32 v6, v5, v6
	v_add_u32_e32 v7, 1, v3
	v_cmp_ge_u32_e32 vcc, v6, v4
	v_add_u32_e32 v5, 1, v5
	s_nop 0
	v_cndmask_b32_e32 v3, v3, v7, vcc
	v_sub_u32_e32 v7, v6, v4
	v_cndmask_b32_e32 v6, v6, v7, vcc
	v_add_u32_e32 v7, 1, v3
	v_cmp_ge_u32_e32 vcc, v6, v4
	s_nop 1
	v_cndmask_b32_e32 v3, v3, v7, vcc
	v_mul_lo_u32 v6, v4, v3
	v_add_u32_e32 v4, v6, v4
	v_cmp_ne_u32_e32 vcc, v5, v4
	s_and_saveexec_b64 s[12:13], vcc
	s_xor_b64 s[12:13], exec, s[12:13]
	s_cbranch_execz .LBB0_663
	s_waitcnt lgkmcnt(0)
	s_add_u32 s20, s84, 0x33400
	s_addc_u32 s21, s85, 0
	v_add_u32_e32 v3, 1, v3
	v_mul_lo_u32 v3, v3, v2
	v_mov_b32_e32 v2, 0
	global_load_dword v2, v2, s[20:21] sc1
	s_waitcnt vmcnt(0)
	v_cmp_lt_u32_e32 vcc, v2, v3
	s_and_saveexec_b64 s[14:15], vcc
	s_cbranch_execz .LBB0_662
	s_add_u32 s16, s84, 0x30200
	s_addc_u32 s17, s85, 0
	s_mov_b32 s33, 1
	s_mov_b64 s[22:23], 0
	v_mov_b32_e32 v2, 0
	s_branch .LBB0_653

; __device__ __forceinline__ unsigned xb_ld(unsigned* p)              { return __hip_atomic_load(p, __ATOMIC_RELAXED, __HIP_MEMORY_SCOPE_AGENT); }
; #define XB_SPIN(cond, bar) do { unsigned _sp = 0; while (cond) { __builtin_amdgcn_s_sleep(1); \
;     if ((++_sp & 255u) == 0u) { if (xb_ld(&(bar)[XB_TMO])) break; if (_sp > XB_SPIN_CAP) { atomicAdd(&(bar)[XB_TMO], 1u); break; } } } } while (0)
; __device__ __forceinline__ void xcd_barrier(const XcdBarrier& b) {
;     ...
;             else XB_SPIN(xb_ld(&bar[XB_TOPGEN]) == tg, bar);
.LBB0_655:
	global_load_dword v4, v2, s[20:21] sc1
	s_add_i32 s33, s33, 1
	s_mov_b64 s[28:29], -1
	s_waitcnt vmcnt(0)
	v_cmp_ge_u32_e32 vcc, v4, v3
	s_orn2_b64 s[26:27], vcc, exec
	s_branch .LBB0_652

; __device__ __forceinline__ unsigned xb_ld(unsigned* p)              { return __hip_atomic_load(p, __ATOMIC_RELAXED, __HIP_MEMORY_SCOPE_AGENT); }
; __device__ __forceinline__ unsigned xb_add(unsigned* p, unsigned v) { return __hip_atomic_fetch_add(p, v, __ATOMIC_RELAXED, __HIP_MEMORY_SCOPE_AGENT); }
; #define XB_SPIN(cond, bar) do { unsigned _sp = 0; while (cond) { __builtin_amdgcn_s_sleep(1); \
;     if ((++_sp & 255u) == 0u) { if (xb_ld(&(bar)[XB_TMO])) break; if (_sp > XB_SPIN_CAP) { atomicAdd(&(bar)[XB_TMO], 1u); break; } } } } while (0)
; __device__ __forceinline__ void xcd_barrier(const XcdBarrier& b) {
;     ...
;             asm volatile("s_waitcnt vmcnt(0)" ::: "memory");
;             const unsigned og = xb_add(&bar[XB_TOP], 1u);
;             const unsigned tg = og / nx;
;             if (og + 1u == (tg + 1u) * nx) xb_add(&bar[XB_TOPGEN], 1u);
;             else XB_SPIN(xb_ld(&bar[XB_TOPGEN]) == tg, bar);
;             __builtin_amdgcn_fence(__ATOMIC_ACQUIRE, "agent");
.LBB0_666:
	s_or_b64 exec, exec, s[14:15]
	v_cvt_f32_u32_e32 v5, v2
	s_waitcnt vmcnt(0)
	v_readfirstlane_b32 s12, v4
	s_add_u32 s14, s84, 0x33500
	s_addc_u32 s15, s85, 0
	v_rcp_iflag_f32_e32 v5, v5
	v_add_u32_e32 v3, s12, v3
	v_add_u32_e32 v6, 1, v3
	s_mov_b64 s[16:17], 0
	v_mul_f32_e32 v4, 0x4f7ffffe, v5
	v_cvt_u32_f32_e32 v4, v4
	v_sub_u32_e32 v5, 0, v2
	v_mul_lo_u32 v5, v5, v4
	v_mul_hi_u32 v5, v4, v5
	v_add_u32_e32 v4, v4, v5
	v_mul_hi_u32 v4, v3, v4
	v_mul_lo_u32 v5, v4, v2
	v_sub_u32_e32 v3, v3, v5
	v_add_u32_e32 v7, 1, v4
	v_cmp_ge_u32_e32 vcc, v3, v2
	v_sub_u32_e32 v5, v3, v2
	s_nop 0
	v_cndmask_b32_e32 v4, v4, v7, vcc
	v_cndmask_b32_e32 v3, v3, v5, vcc
	v_add_u32_e32 v5, 1, v4
	v_cmp_ge_u32_e32 vcc, v3, v2
	s_nop 1
	v_cndmask_b32_e32 v4, v4, v5, vcc
	v_mul_lo_u32 v3, v2, v4
	v_add_u32_e32 v2, v3, v2
	v_mov_b32_e32 v8, v2
	v_cmp_ne_u32_e32 vcc, v6, v2
	v_mov_b64_e32 v[2:3], s[14:15]
	s_and_saveexec_b64 s[12:13], vcc
	s_cbranch_execz .LBB0_678
	s_add_u32 s100, s84, 0x33400
	s_addc_u32 s101, s85, 0
	v_mov_b32_e32 v2, 0
	global_load_dword v3, v2, s[100:101] sc1
	s_mov_b64 s[22:23], 0
	s_waitcnt vmcnt(0)
	v_cmp_lt_u32_e32 vcc, v3, v8
	s_and_saveexec_b64 s[20:21], vcc
	s_cbranch_execz .LBB0_677
	s_add_u32 s16, s84, 0x30200
	s_addc_u32 s17, s85, 0
	s_mov_b32 s33, 1
	s_branch .LBB0_670

; __device__ __forceinline__ unsigned xb_ld(unsigned* p)              { return __hip_atomic_load(p, __ATOMIC_RELAXED, __HIP_MEMORY_SCOPE_AGENT); }
; #define XB_SPIN(cond, bar) do { unsigned _sp = 0; while (cond) { __builtin_amdgcn_s_sleep(1); \
;     if ((++_sp & 255u) == 0u) { if (xb_ld(&(bar)[XB_TMO])) break; if (_sp > XB_SPIN_CAP) { atomicAdd(&(bar)[XB_TMO], 1u); break; } } } } while (0)
; __device__ __forceinline__ void xcd_barrier(const XcdBarrier& b) {
;     ...
;             else XB_SPIN(xb_ld(&bar[XB_TOPGEN]) == tg, bar);
.LBB0_672:
	global_load_dword v3, v2, s[100:101] sc1
	s_add_i32 s33, s33, 1
	s_mov_b64 s[26:27], -1
	s_waitcnt vmcnt(0)
	v_cmp_ge_u32_e32 vcc, v3, v8
	s_orn2_b64 s[30:31], vcc, exec
	s_branch .LBB0_669

; __device__ __forceinline__ unsigned xb_ld(unsigned* p)              { return __hip_atomic_load(p, __ATOMIC_RELAXED, __HIP_MEMORY_SCOPE_AGENT); }
; __device__ __forceinline__ unsigned xb_add(unsigned* p, unsigned v) { return __hip_atomic_fetch_add(p, v, __ATOMIC_RELAXED, __HIP_MEMORY_SCOPE_AGENT); }
; #define XB_SPIN(cond, bar) do { unsigned _sp = 0; while (cond) { __builtin_amdgcn_s_sleep(1); \
;     if ((++_sp & 255u) == 0u) { if (xb_ld(&(bar)[XB_TMO])) break; if (_sp > XB_SPIN_CAP) { atomicAdd(&(bar)[XB_TMO], 1u); break; } } } } while (0)
; __device__ __forceinline__ void xcd_barrier(const XcdBarrier& b) {
;     ...
;         const unsigned old = xb_add(&bar[XB_XSUB(b.x)], 1u);
;         const unsigned gen = old / nloc;
;         if (old + 1u == (gen + 1u) * nloc) {
;             __builtin_amdgcn_fence(__ATOMIC_RELEASE, "agent");
;             asm volatile("s_waitcnt vmcnt(0)" ::: "memory");
;             const unsigned og = xb_add(&bar[XB_TOP], 1u);
;             const unsigned tg = og / nx;
;             if (og + 1u == (tg + 1u) * nx) xb_add(&bar[XB_TOPGEN], 1u);
;             else XB_SPIN(xb_ld(&bar[XB_TOPGEN]) == tg, bar);
;             __builtin_amdgcn_fence(__ATOMIC_ACQUIRE, "agent");
;             xb_add(&bar[XB_XGEN(b.x)], 1u);
;             asm volatile("s_waitcnt vmcnt(0)" ::: "memory");
;         } else {
;             XB_SPIN(xb_ld(&bar[XB_XGEN(b.x)]) == gen, bar);
.LBB0_974:
	v_readlane_b32 s4, v254, 16
	s_lshl_b32 s4, s4, 8
	v_readlane_b32 s6, v254, 12
	v_readlane_b32 s7, v254, 13
	s_add_u32 s4, s6, s4
	s_addc_u32 s5, s7, 0
	v_mov_b32_e32 v3, 0x1000
	v_mov_b32_e32 v5, 1
	global_atomic_add v5, v3, v5, s[4:5] offset:1024 sc0
	v_cvt_f32_u32_e32 v3, v4
	v_sub_u32_e32 v6, 0, v4
	v_rcp_iflag_f32_e32 v3, v3
	s_nop 0
	v_mul_f32_e32 v3, 0x4f7ffffe, v3
	v_cvt_u32_f32_e32 v3, v3
	v_mul_lo_u32 v6, v6, v3
	v_mul_hi_u32 v6, v3, v6
	v_add_u32_e32 v3, v3, v6
	s_waitcnt vmcnt(0)
	v_mul_hi_u32 v3, v5, v3
	v_mul_lo_u32 v6, v3, v4
	v_sub_u32_e32 v6, v5, v6
	v_add_u32_e32 v7, 1, v3
	v_cmp_ge_u32_e32 vcc, v6, v4
	v_add_u32_e32 v5, 1, v5
	s_nop 0
	v_cndmask_b32_e32 v3, v3, v7, vcc
	v_sub_u32_e32 v7, v6, v4
	v_cndmask_b32_e32 v6, v6, v7, vcc
	v_add_u32_e32 v7, 1, v3
	v_cmp_ge_u32_e32 vcc, v6, v4
	s_nop 1
	v_cndmask_b32_e32 v3, v3, v7, vcc
	v_mul_lo_u32 v6, v4, v3
	v_add_u32_e32 v4, v6, v4
	v_cmp_ne_u32_e32 vcc, v5, v4
	s_and_saveexec_b64 s[6:7], vcc
	s_xor_b64 s[6:7], exec, s[6:7]
	s_cbranch_execz .LBB0_988
	s_waitcnt lgkmcnt(0)
	s_add_u32 s14, s84, 0x33400
	s_addc_u32 s15, s85, 0
	v_add_u32_e32 v3, 1, v3
	v_mul_lo_u32 v3, v3, v2
	v_mov_b32_e32 v2, 0
	global_load_dword v2, v2, s[14:15] sc1
	s_waitcnt vmcnt(0)
	v_cmp_lt_u32_e32 vcc, v2, v3
	s_and_saveexec_b64 s[8:9], vcc
	s_cbranch_execz .LBB0_987
	s_add_u32 s10, s84, 0x30200
	s_addc_u32 s11, s85, 0
	s_mov_b32 s26, 1
	s_mov_b64 s[16:17], 0
	v_mov_b32_e32 v2, 0
	s_branch .LBB0_978

; __device__ __forceinline__ unsigned xb_ld(unsigned* p)              { return __hip_atomic_load(p, __ATOMIC_RELAXED, __HIP_MEMORY_SCOPE_AGENT); }
; #define XB_SPIN(cond, bar) do { unsigned _sp = 0; while (cond) { __builtin_amdgcn_s_sleep(1); \
;     if ((++_sp & 255u) == 0u) { if (xb_ld(&(bar)[XB_TMO])) break; if (_sp > XB_SPIN_CAP) { atomicAdd(&(bar)[XB_TMO], 1u); break; } } } } while (0)
; __device__ __forceinline__ void xcd_barrier(const XcdBarrier& b) {
;     ...
;             else XB_SPIN(xb_ld(&bar[XB_TOPGEN]) == tg, bar);
.LBB0_980:
	global_load_dword v4, v2, s[14:15] sc1
	s_add_i32 s26, s26, 1
	s_mov_b64 s[22:23], -1
	s_waitcnt vmcnt(0)
	v_cmp_ge_u32_e32 vcc, v4, v3
	s_orn2_b64 s[20:21], vcc, exec
	s_branch .LBB0_977

; __device__ __forceinline__ unsigned xb_ld(unsigned* p)              { return __hip_atomic_load(p, __ATOMIC_RELAXED, __HIP_MEMORY_SCOPE_AGENT); }
; __device__ __forceinline__ unsigned xb_add(unsigned* p, unsigned v) { return __hip_atomic_fetch_add(p, v, __ATOMIC_RELAXED, __HIP_MEMORY_SCOPE_AGENT); }
; #define XB_SPIN(cond, bar) do { unsigned _sp = 0; while (cond) { __builtin_amdgcn_s_sleep(1); \
;     if ((++_sp & 255u) == 0u) { if (xb_ld(&(bar)[XB_TMO])) break; if (_sp > XB_SPIN_CAP) { atomicAdd(&(bar)[XB_TMO], 1u); break; } } } } while (0)
; __device__ __forceinline__ void xcd_barrier(const XcdBarrier& b) {
;     ...
;             asm volatile("s_waitcnt vmcnt(0)" ::: "memory");
;             const unsigned og = xb_add(&bar[XB_TOP], 1u);
;             const unsigned tg = og / nx;
;             if (og + 1u == (tg + 1u) * nx) xb_add(&bar[XB_TOPGEN], 1u);
;             else XB_SPIN(xb_ld(&bar[XB_TOPGEN]) == tg, bar);
;             __builtin_amdgcn_fence(__ATOMIC_ACQUIRE, "agent");
.LBB0_991:
	s_or_b64 exec, exec, s[8:9]
	v_cvt_f32_u32_e32 v5, v2
	s_waitcnt vmcnt(0)
	v_readfirstlane_b32 s6, v4
	s_add_u32 s8, s84, 0x33500
	s_addc_u32 s9, s85, 0
	v_rcp_iflag_f32_e32 v5, v5
	v_add_u32_e32 v3, s6, v3
	v_add_u32_e32 v6, 1, v3
	s_mov_b64 s[10:11], 0
	v_mul_f32_e32 v4, 0x4f7ffffe, v5
	v_cvt_u32_f32_e32 v4, v4
	v_sub_u32_e32 v5, 0, v2
	v_mul_lo_u32 v5, v5, v4
	v_mul_hi_u32 v5, v4, v5
	v_add_u32_e32 v4, v4, v5
	v_mul_hi_u32 v4, v3, v4
	v_mul_lo_u32 v5, v4, v2
	v_sub_u32_e32 v3, v3, v5
	v_add_u32_e32 v7, 1, v4
	v_cmp_ge_u32_e32 vcc, v3, v2
	v_sub_u32_e32 v5, v3, v2
	s_nop 0
	v_cndmask_b32_e32 v4, v4, v7, vcc
	v_cndmask_b32_e32 v3, v3, v5, vcc
	v_add_u32_e32 v5, 1, v4
	v_cmp_ge_u32_e32 vcc, v3, v2
	s_nop 1
	v_cndmask_b32_e32 v4, v4, v5, vcc
	v_mul_lo_u32 v3, v2, v4
	v_add_u32_e32 v2, v3, v2
	v_mov_b32_e32 v8, v2
	v_cmp_ne_u32_e32 vcc, v6, v2
	v_mov_b64_e32 v[2:3], s[8:9]
	s_and_saveexec_b64 s[6:7], vcc
	s_cbranch_execz .LBB0_1003
	s_add_u32 s100, s84, 0x33400
	s_addc_u32 s101, s85, 0
	v_mov_b32_e32 v2, 0
	global_load_dword v3, v2, s[100:101] sc1
	s_mov_b64 s[16:17], 0
	s_waitcnt vmcnt(0)
	v_cmp_lt_u32_e32 vcc, v3, v8
	s_and_saveexec_b64 s[14:15], vcc
	s_cbranch_execz .LBB0_1002
	s_add_u32 s10, s84, 0x30200
	s_addc_u32 s11, s85, 0
	s_mov_b32 s26, 1
	s_branch .LBB0_995

; __device__ __forceinline__ unsigned xb_ld(unsigned* p)              { return __hip_atomic_load(p, __ATOMIC_RELAXED, __HIP_MEMORY_SCOPE_AGENT); }
; #define XB_SPIN(cond, bar) do { unsigned _sp = 0; while (cond) { __builtin_amdgcn_s_sleep(1); \
;     if ((++_sp & 255u) == 0u) { if (xb_ld(&(bar)[XB_TMO])) break; if (_sp > XB_SPIN_CAP) { atomicAdd(&(bar)[XB_TMO], 1u); break; } } } } while (0)
; __device__ __forceinline__ void xcd_barrier(const XcdBarrier& b) {
;     ...
;             else XB_SPIN(xb_ld(&bar[XB_TOPGEN]) == tg, bar);
.LBB0_997:
	global_load_dword v3, v2, s[100:101] sc1
	s_add_i32 s26, s26, 1
	s_mov_b64 s[20:21], -1
	s_waitcnt vmcnt(0)
	v_cmp_ge_u32_e32 vcc, v3, v8
	s_orn2_b64 s[24:25], vcc, exec
	s_branch .LBB0_994

; __device__ __forceinline__ unsigned xb_add(unsigned* p, unsigned v) { return __hip_atomic_fetch_add(p, v, __ATOMIC_RELAXED, __HIP_MEMORY_SCOPE_AGENT); }
; __device__ __forceinline__ void xcd_barrier(const XcdBarrier& b) {
;     ...
;             __builtin_amdgcn_fence(__ATOMIC_ACQUIRE, "agent");
;             xb_add(&bar[XB_XGEN(b.x)], 1u);
;             asm volatile("s_waitcnt vmcnt(0)" ::: "memory");
.LBB0_1005:
	s_or_b64 exec, exec, s[6:7]
	v_mov_b32_e32 v2, 0x2000
	v_mov_b32_e32 v3, 1
	s_waitcnt vmcnt(0)
	s_waitcnt vmcnt(0)
	s_branch .LBB0_1006

; __device__ __forceinline__ unsigned xb_ld(unsigned* p)              { return __hip_atomic_load(p, __ATOMIC_RELAXED, __HIP_MEMORY_SCOPE_AGENT); }
; __device__ __forceinline__ unsigned xb_add(unsigned* p, unsigned v) { return __hip_atomic_fetch_add(p, v, __ATOMIC_RELAXED, __HIP_MEMORY_SCOPE_AGENT); }
; #define XB_SPIN(cond, bar) do { unsigned _sp = 0; while (cond) { __builtin_amdgcn_s_sleep(1); \
;     if ((++_sp & 255u) == 0u) { if (xb_ld(&(bar)[XB_TMO])) break; if (_sp > XB_SPIN_CAP) { atomicAdd(&(bar)[XB_TMO], 1u); break; } } } } while (0)
; __device__ __forceinline__ void xcd_barrier(const XcdBarrier& b) {
;     ...
;         const unsigned old = xb_add(&bar[XB_XSUB(b.x)], 1u);
;         const unsigned gen = old / nloc;
;         if (old + 1u == (gen + 1u) * nloc) {
;             __builtin_amdgcn_fence(__ATOMIC_RELEASE, "agent");
;             asm volatile("s_waitcnt vmcnt(0)" ::: "memory");
;             const unsigned og = xb_add(&bar[XB_TOP], 1u);
;             const unsigned tg = og / nx;
;             if (og + 1u == (tg + 1u) * nx) xb_add(&bar[XB_TOPGEN], 1u);
;             else XB_SPIN(xb_ld(&bar[XB_TOPGEN]) == tg, bar);
;             __builtin_amdgcn_fence(__ATOMIC_ACQUIRE, "agent");
;             xb_add(&bar[XB_XGEN(b.x)], 1u);
;             asm volatile("s_waitcnt vmcnt(0)" ::: "memory");
;         } else {
;             XB_SPIN(xb_ld(&bar[XB_XGEN(b.x)]) == gen, bar);
.LBB0_1101:
	v_readlane_b32 s4, v254, 16
	s_lshl_b32 s4, s4, 8
	v_readlane_b32 s6, v254, 12
	v_readlane_b32 s7, v254, 13
	s_add_u32 s4, s6, s4
	s_addc_u32 s5, s7, 0
	v_mov_b32_e32 v3, 0x1000
	v_mov_b32_e32 v5, 1
	global_atomic_add v5, v3, v5, s[4:5] offset:1024 sc0
	v_cvt_f32_u32_e32 v3, v4
	v_sub_u32_e32 v6, 0, v4
	v_rcp_iflag_f32_e32 v3, v3
	s_nop 0
	v_mul_f32_e32 v3, 0x4f7ffffe, v3
	v_cvt_u32_f32_e32 v3, v3
	v_mul_lo_u32 v6, v6, v3
	v_mul_hi_u32 v6, v3, v6
	v_add_u32_e32 v3, v3, v6
	s_waitcnt vmcnt(0)
	v_mul_hi_u32 v3, v5, v3
	v_mul_lo_u32 v6, v3, v4
	v_sub_u32_e32 v6, v5, v6
	v_add_u32_e32 v7, 1, v3
	v_cmp_ge_u32_e32 vcc, v6, v4
	v_add_u32_e32 v5, 1, v5
	s_nop 0
	v_cndmask_b32_e32 v3, v3, v7, vcc
	v_sub_u32_e32 v7, v6, v4
	v_cndmask_b32_e32 v6, v6, v7, vcc
	v_add_u32_e32 v7, 1, v3
	v_cmp_ge_u32_e32 vcc, v6, v4
	s_nop 1
	v_cndmask_b32_e32 v3, v3, v7, vcc
	v_mul_lo_u32 v6, v4, v3
	v_add_u32_e32 v4, v6, v4
	v_cmp_ne_u32_e32 vcc, v5, v4
	s_and_saveexec_b64 s[6:7], vcc
	s_xor_b64 s[6:7], exec, s[6:7]
	s_cbranch_execz .LBB0_1115
	s_waitcnt lgkmcnt(0)
	s_add_u32 s12, s84, 0x33400
	s_addc_u32 s13, s85, 0
	v_add_u32_e32 v3, 1, v3
	v_mul_lo_u32 v3, v3, v2
	v_mov_b32_e32 v2, 0
	global_load_dword v2, v2, s[12:13] sc1
	s_waitcnt vmcnt(0)
	v_cmp_lt_u32_e32 vcc, v2, v3
	s_and_saveexec_b64 s[8:9], vcc
	s_cbranch_execz .LBB0_1114
	s_add_u32 s10, s84, 0x30200
	s_addc_u32 s11, s85, 0
	s_mov_b32 s24, 1
	s_mov_b64 s[14:15], 0
	v_mov_b32_e32 v2, 0
	s_branch .LBB0_1105

; __device__ __forceinline__ unsigned xb_ld(unsigned* p)              { return __hip_atomic_load(p, __ATOMIC_RELAXED, __HIP_MEMORY_SCOPE_AGENT); }
; #define XB_SPIN(cond, bar) do { unsigned _sp = 0; while (cond) { __builtin_amdgcn_s_sleep(1); \
;     if ((++_sp & 255u) == 0u) { if (xb_ld(&(bar)[XB_TMO])) break; if (_sp > XB_SPIN_CAP) { atomicAdd(&(bar)[XB_TMO], 1u); break; } } } } while (0)
; __device__ __forceinline__ void xcd_barrier(const XcdBarrier& b) {
;     ...
;             else XB_SPIN(xb_ld(&bar[XB_TOPGEN]) == tg, bar);
.LBB0_1107:
	global_load_dword v4, v2, s[12:13] sc1
	s_add_i32 s24, s24, 1
	s_mov_b64 s[20:21], -1
	s_waitcnt vmcnt(0)
	v_cmp_ge_u32_e32 vcc, v4, v3
	s_orn2_b64 s[18:19], vcc, exec
	s_branch .LBB0_1104

; __device__ __forceinline__ unsigned xb_ld(unsigned* p)              { return __hip_atomic_load(p, __ATOMIC_RELAXED, __HIP_MEMORY_SCOPE_AGENT); }
; __device__ __forceinline__ unsigned xb_add(unsigned* p, unsigned v) { return __hip_atomic_fetch_add(p, v, __ATOMIC_RELAXED, __HIP_MEMORY_SCOPE_AGENT); }
; #define XB_SPIN(cond, bar) do { unsigned _sp = 0; while (cond) { __builtin_amdgcn_s_sleep(1); \
;     if ((++_sp & 255u) == 0u) { if (xb_ld(&(bar)[XB_TMO])) break; if (_sp > XB_SPIN_CAP) { atomicAdd(&(bar)[XB_TMO], 1u); break; } } } } while (0)
; __device__ __forceinline__ void xcd_barrier(const XcdBarrier& b) {
;     ...
;             asm volatile("s_waitcnt vmcnt(0)" ::: "memory");
;             const unsigned og = xb_add(&bar[XB_TOP], 1u);
;             const unsigned tg = og / nx;
;             if (og + 1u == (tg + 1u) * nx) xb_add(&bar[XB_TOPGEN], 1u);
;             else XB_SPIN(xb_ld(&bar[XB_TOPGEN]) == tg, bar);
;             __builtin_amdgcn_fence(__ATOMIC_ACQUIRE, "agent");
.LBB0_1118:
	s_or_b64 exec, exec, s[8:9]
	v_cvt_f32_u32_e32 v5, v2
	s_waitcnt vmcnt(0)
	v_readfirstlane_b32 s6, v4
	s_add_u32 s8, s84, 0x33500
	s_addc_u32 s9, s85, 0
	v_rcp_iflag_f32_e32 v5, v5
	v_add_u32_e32 v3, s6, v3
	v_add_u32_e32 v6, 1, v3
	s_mov_b64 s[10:11], 0
	v_mul_f32_e32 v4, 0x4f7ffffe, v5
	v_cvt_u32_f32_e32 v4, v4
	v_sub_u32_e32 v5, 0, v2
	v_mul_lo_u32 v5, v5, v4
	v_mul_hi_u32 v5, v4, v5
	v_add_u32_e32 v4, v4, v5
	v_mul_hi_u32 v4, v3, v4
	v_mul_lo_u32 v5, v4, v2
	v_sub_u32_e32 v3, v3, v5
	v_add_u32_e32 v7, 1, v4
	v_cmp_ge_u32_e32 vcc, v3, v2
	v_sub_u32_e32 v5, v3, v2
	s_nop 0
	v_cndmask_b32_e32 v4, v4, v7, vcc
	v_cndmask_b32_e32 v3, v3, v5, vcc
	v_add_u32_e32 v5, 1, v4
	v_cmp_ge_u32_e32 vcc, v3, v2
	s_nop 1
	v_cndmask_b32_e32 v4, v4, v5, vcc
	v_mul_lo_u32 v3, v2, v4
	v_add_u32_e32 v2, v3, v2
	v_mov_b32_e32 v8, v2
	v_cmp_ne_u32_e32 vcc, v6, v2
	v_mov_b64_e32 v[2:3], s[8:9]
	s_and_saveexec_b64 s[6:7], vcc
	s_cbranch_execz .LBB0_1130
	s_add_u32 s100, s84, 0x33400
	s_addc_u32 s101, s85, 0
	v_mov_b32_e32 v2, 0
	global_load_dword v3, v2, s[100:101] sc1
	s_mov_b64 s[14:15], 0
	s_waitcnt vmcnt(0)
	v_cmp_lt_u32_e32 vcc, v3, v8
	s_and_saveexec_b64 s[12:13], vcc
	s_cbranch_execz .LBB0_1129
	s_add_u32 s10, s84, 0x30200
	s_addc_u32 s11, s85, 0
	s_mov_b32 s24, 1
	s_branch .LBB0_1122

; __device__ __forceinline__ unsigned xb_ld(unsigned* p)              { return __hip_atomic_load(p, __ATOMIC_RELAXED, __HIP_MEMORY_SCOPE_AGENT); }
; #define XB_SPIN(cond, bar) do { unsigned _sp = 0; while (cond) { __builtin_amdgcn_s_sleep(1); \
;     if ((++_sp & 255u) == 0u) { if (xb_ld(&(bar)[XB_TMO])) break; if (_sp > XB_SPIN_CAP) { atomicAdd(&(bar)[XB_TMO], 1u); break; } } } } while (0)
; __device__ __forceinline__ void xcd_barrier(const XcdBarrier& b) {
;     ...
;             else XB_SPIN(xb_ld(&bar[XB_TOPGEN]) == tg, bar);
.LBB0_1124:
	global_load_dword v3, v2, s[100:101] sc1
	s_add_i32 s24, s24, 1
	s_mov_b64 s[18:19], -1
	s_waitcnt vmcnt(0)
	v_cmp_ge_u32_e32 vcc, v3, v8
	s_orn2_b64 s[22:23], vcc, exec
	s_branch .LBB0_1121

; __device__ __forceinline__ unsigned xb_ld(unsigned* p)              { return __hip_atomic_load(p, __ATOMIC_RELAXED, __HIP_MEMORY_SCOPE_AGENT); }
; __device__ __forceinline__ unsigned xb_add(unsigned* p, unsigned v) { return __hip_atomic_fetch_add(p, v, __ATOMIC_RELAXED, __HIP_MEMORY_SCOPE_AGENT); }
; #define XB_SPIN(cond, bar) do { unsigned _sp = 0; while (cond) { __builtin_amdgcn_s_sleep(1); \
;     if ((++_sp & 255u) == 0u) { if (xb_ld(&(bar)[XB_TMO])) break; if (_sp > XB_SPIN_CAP) { atomicAdd(&(bar)[XB_TMO], 1u); break; } } } } while (0)
; __device__ __forceinline__ void xcd_barrier(const XcdBarrier& b) {
;     ...
;         const unsigned old = xb_add(&bar[XB_XSUB(b.x)], 1u);
;         const unsigned gen = old / nloc;
;         if (old + 1u == (gen + 1u) * nloc) {
;             __builtin_amdgcn_fence(__ATOMIC_RELEASE, "agent");
;             asm volatile("s_waitcnt vmcnt(0)" ::: "memory");
;             const unsigned og = xb_add(&bar[XB_TOP], 1u);
;             const unsigned tg = og / nx;
;             if (og + 1u == (tg + 1u) * nx) xb_add(&bar[XB_TOPGEN], 1u);
;             else XB_SPIN(xb_ld(&bar[XB_TOPGEN]) == tg, bar);
;             __builtin_amdgcn_fence(__ATOMIC_ACQUIRE, "agent");
;             xb_add(&bar[XB_XGEN(b.x)], 1u);
;             asm volatile("s_waitcnt vmcnt(0)" ::: "memory");
;         } else {
;             XB_SPIN(xb_ld(&bar[XB_XGEN(b.x)]) == gen, bar);
.LBB0_1371:
	v_readlane_b32 s8, v254, 16
	s_lshl_b32 s8, s8, 8
	v_readlane_b32 s10, v254, 12
	v_readlane_b32 s11, v254, 13
	s_add_u32 s8, s10, s8
	s_addc_u32 s9, s11, 0
	v_mov_b32_e32 v3, 0x1000
	v_mov_b32_e32 v5, 1
	global_atomic_add v5, v3, v5, s[8:9] offset:1024 sc0
	v_cvt_f32_u32_e32 v3, v4
	v_sub_u32_e32 v6, 0, v4
	v_rcp_iflag_f32_e32 v3, v3
	s_nop 0
	v_mul_f32_e32 v3, 0x4f7ffffe, v3
	v_cvt_u32_f32_e32 v3, v3
	v_mul_lo_u32 v6, v6, v3
	v_mul_hi_u32 v6, v3, v6
	v_add_u32_e32 v3, v3, v6
	s_waitcnt vmcnt(0)
	v_mul_hi_u32 v3, v5, v3
	v_mul_lo_u32 v6, v3, v4
	v_sub_u32_e32 v6, v5, v6
	v_add_u32_e32 v7, 1, v3
	v_cmp_ge_u32_e32 vcc, v6, v4
	v_add_u32_e32 v5, 1, v5
	s_nop 0
	v_cndmask_b32_e32 v3, v3, v7, vcc
	v_sub_u32_e32 v7, v6, v4
	v_cndmask_b32_e32 v6, v6, v7, vcc
	v_add_u32_e32 v7, 1, v3
	v_cmp_ge_u32_e32 vcc, v6, v4
	s_nop 1
	v_cndmask_b32_e32 v3, v3, v7, vcc
	v_mul_lo_u32 v6, v4, v3
	v_add_u32_e32 v4, v6, v4
	v_cmp_ne_u32_e32 vcc, v5, v4
	s_and_saveexec_b64 s[10:11], vcc
	s_xor_b64 s[10:11], exec, s[10:11]
	s_cbranch_execz .LBB0_1385
	s_waitcnt lgkmcnt(0)
	s_add_u32 s16, s84, 0x33400
	s_addc_u32 s17, s85, 0
	v_add_u32_e32 v3, 1, v3
	v_mul_lo_u32 v3, v3, v2
	v_mov_b32_e32 v2, 0
	global_load_dword v2, v2, s[16:17] sc1
	s_waitcnt vmcnt(0)
	v_cmp_lt_u32_e32 vcc, v2, v3
	s_and_saveexec_b64 s[12:13], vcc
	s_cbranch_execz .LBB0_1384
	s_add_u32 s14, s84, 0x30200
	s_addc_u32 s15, s85, 0
	s_mov_b32 s28, 1
	s_mov_b64 s[18:19], 0
	v_mov_b32_e32 v2, 0
	s_branch .LBB0_1375

; __device__ __forceinline__ unsigned xb_ld(unsigned* p)              { return __hip_atomic_load(p, __ATOMIC_RELAXED, __HIP_MEMORY_SCOPE_AGENT); }
; #define XB_SPIN(cond, bar) do { unsigned _sp = 0; while (cond) { __builtin_amdgcn_s_sleep(1); \
;     if ((++_sp & 255u) == 0u) { if (xb_ld(&(bar)[XB_TMO])) break; if (_sp > XB_SPIN_CAP) { atomicAdd(&(bar)[XB_TMO], 1u); break; } } } } while (0)
; __device__ __forceinline__ void xcd_barrier(const XcdBarrier& b) {
;     ...
;             else XB_SPIN(xb_ld(&bar[XB_TOPGEN]) == tg, bar);
.LBB0_1377:
	global_load_dword v4, v2, s[16:17] sc1
	s_add_i32 s28, s28, 1
	s_mov_b64 s[24:25], -1
	s_waitcnt vmcnt(0)
	v_cmp_ge_u32_e32 vcc, v4, v3
	s_orn2_b64 s[22:23], vcc, exec
	s_branch .LBB0_1374

; __device__ __forceinline__ unsigned xb_ld(unsigned* p)              { return __hip_atomic_load(p, __ATOMIC_RELAXED, __HIP_MEMORY_SCOPE_AGENT); }
; __device__ __forceinline__ unsigned xb_add(unsigned* p, unsigned v) { return __hip_atomic_fetch_add(p, v, __ATOMIC_RELAXED, __HIP_MEMORY_SCOPE_AGENT); }
; #define XB_SPIN(cond, bar) do { unsigned _sp = 0; while (cond) { __builtin_amdgcn_s_sleep(1); \
;     if ((++_sp & 255u) == 0u) { if (xb_ld(&(bar)[XB_TMO])) break; if (_sp > XB_SPIN_CAP) { atomicAdd(&(bar)[XB_TMO], 1u); break; } } } } while (0)
; __device__ __forceinline__ void xcd_barrier(const XcdBarrier& b) {
;     ...
;             asm volatile("s_waitcnt vmcnt(0)" ::: "memory");
;             const unsigned og = xb_add(&bar[XB_TOP], 1u);
;             const unsigned tg = og / nx;
;             if (og + 1u == (tg + 1u) * nx) xb_add(&bar[XB_TOPGEN], 1u);
;             else XB_SPIN(xb_ld(&bar[XB_TOPGEN]) == tg, bar);
;             __builtin_amdgcn_fence(__ATOMIC_ACQUIRE, "agent");
.LBB0_1388:
	s_or_b64 exec, exec, s[12:13]
	v_cvt_f32_u32_e32 v5, v2
	s_waitcnt vmcnt(0)
	v_readfirstlane_b32 s10, v4
	s_add_u32 s12, s84, 0x33500
	s_addc_u32 s13, s85, 0
	v_rcp_iflag_f32_e32 v5, v5
	v_add_u32_e32 v3, s10, v3
	v_add_u32_e32 v6, 1, v3
	s_mov_b64 s[14:15], 0
	v_mul_f32_e32 v4, 0x4f7ffffe, v5
	v_cvt_u32_f32_e32 v4, v4
	v_sub_u32_e32 v5, 0, v2
	v_mul_lo_u32 v5, v5, v4
	v_mul_hi_u32 v5, v4, v5
	v_add_u32_e32 v4, v4, v5
	v_mul_hi_u32 v4, v3, v4
	v_mul_lo_u32 v5, v4, v2
	v_sub_u32_e32 v3, v3, v5
	v_add_u32_e32 v7, 1, v4
	v_cmp_ge_u32_e32 vcc, v3, v2
	v_sub_u32_e32 v5, v3, v2
	s_nop 0
	v_cndmask_b32_e32 v4, v4, v7, vcc
	v_cndmask_b32_e32 v3, v3, v5, vcc
	v_add_u32_e32 v5, 1, v4
	v_cmp_ge_u32_e32 vcc, v3, v2
	s_nop 1
	v_cndmask_b32_e32 v4, v4, v5, vcc
	v_mul_lo_u32 v3, v2, v4
	v_add_u32_e32 v2, v3, v2
	v_mov_b32_e32 v8, v2
	v_cmp_ne_u32_e32 vcc, v6, v2
	v_mov_b64_e32 v[2:3], s[12:13]
	s_and_saveexec_b64 s[10:11], vcc
	s_cbranch_execz .LBB0_1400
	s_add_u32 s100, s84, 0x33400
	s_addc_u32 s101, s85, 0
	v_mov_b32_e32 v2, 0
	global_load_dword v3, v2, s[100:101] sc1
	s_mov_b64 s[18:19], 0
	s_waitcnt vmcnt(0)
	v_cmp_lt_u32_e32 vcc, v3, v8
	s_and_saveexec_b64 s[16:17], vcc
	s_cbranch_execz .LBB0_1399
	s_add_u32 s14, s84, 0x30200
	s_addc_u32 s15, s85, 0
	s_mov_b32 s28, 1
	s_branch .LBB0_1392

; __device__ __forceinline__ unsigned xb_ld(unsigned* p)              { return __hip_atomic_load(p, __ATOMIC_RELAXED, __HIP_MEMORY_SCOPE_AGENT); }
; #define XB_SPIN(cond, bar) do { unsigned _sp = 0; while (cond) { __builtin_amdgcn_s_sleep(1); \
;     if ((++_sp & 255u) == 0u) { if (xb_ld(&(bar)[XB_TMO])) break; if (_sp > XB_SPIN_CAP) { atomicAdd(&(bar)[XB_TMO], 1u); break; } } } } while (0)
; __device__ __forceinline__ void xcd_barrier(const XcdBarrier& b) {
;     ...
;             else XB_SPIN(xb_ld(&bar[XB_TOPGEN]) == tg, bar);
.LBB0_1394:
	global_load_dword v3, v2, s[100:101] sc1
	s_add_i32 s28, s28, 1
	s_mov_b64 s[22:23], -1
	s_waitcnt vmcnt(0)
	v_cmp_ge_u32_e32 vcc, v3, v8
	s_orn2_b64 s[26:27], vcc, exec
	s_branch .LBB0_1391

; __device__ __forceinline__ unsigned xb_ld(unsigned* p)              { return __hip_atomic_load(p, __ATOMIC_RELAXED, __HIP_MEMORY_SCOPE_AGENT); }
; __device__ __forceinline__ unsigned xb_add(unsigned* p, unsigned v) { return __hip_atomic_fetch_add(p, v, __ATOMIC_RELAXED, __HIP_MEMORY_SCOPE_AGENT); }
; #define XB_SPIN(cond, bar) do { unsigned _sp = 0; while (cond) { __builtin_amdgcn_s_sleep(1); \
;     if ((++_sp & 255u) == 0u) { if (xb_ld(&(bar)[XB_TMO])) break; if (_sp > XB_SPIN_CAP) { atomicAdd(&(bar)[XB_TMO], 1u); break; } } } } while (0)
; __device__ __forceinline__ void xcd_barrier(const XcdBarrier& b) {
;     ...
;         const unsigned old = xb_add(&bar[XB_XSUB(b.x)], 1u);
;         const unsigned gen = old / nloc;
;         if (old + 1u == (gen + 1u) * nloc) {
;             __builtin_amdgcn_fence(__ATOMIC_RELEASE, "agent");
;             asm volatile("s_waitcnt vmcnt(0)" ::: "memory");
;             const unsigned og = xb_add(&bar[XB_TOP], 1u);
;             const unsigned tg = og / nx;
;             if (og + 1u == (tg + 1u) * nx) xb_add(&bar[XB_TOPGEN], 1u);
;             else XB_SPIN(xb_ld(&bar[XB_TOPGEN]) == tg, bar);
;             __builtin_amdgcn_fence(__ATOMIC_ACQUIRE, "agent");
;             xb_add(&bar[XB_XGEN(b.x)], 1u);
;             asm volatile("s_waitcnt vmcnt(0)" ::: "memory");
;         } else {
;             XB_SPIN(xb_ld(&bar[XB_XGEN(b.x)]) == gen, bar);
.LBB0_1462:
	v_readlane_b32 s6, v254, 16
	s_lshl_b32 s6, s6, 8
	v_readlane_b32 s8, v254, 12
	v_readlane_b32 s9, v254, 13
	s_add_u32 s6, s8, s6
	s_addc_u32 s7, s9, 0
	v_mov_b32_e32 v3, 0x1000
	v_mov_b32_e32 v5, 1
	global_atomic_add v5, v3, v5, s[6:7] offset:1024 sc0
	v_cvt_f32_u32_e32 v3, v4
	v_sub_u32_e32 v6, 0, v4
	v_rcp_iflag_f32_e32 v3, v3
	s_nop 0
	v_mul_f32_e32 v3, 0x4f7ffffe, v3
	v_cvt_u32_f32_e32 v3, v3
	v_mul_lo_u32 v6, v6, v3
	v_mul_hi_u32 v6, v3, v6
	v_add_u32_e32 v3, v3, v6
	s_waitcnt vmcnt(0)
	v_mul_hi_u32 v3, v5, v3
	v_mul_lo_u32 v6, v3, v4
	v_sub_u32_e32 v6, v5, v6
	v_add_u32_e32 v7, 1, v3
	v_cmp_ge_u32_e32 vcc, v6, v4
	v_add_u32_e32 v5, 1, v5
	s_nop 0
	v_cndmask_b32_e32 v3, v3, v7, vcc
	v_sub_u32_e32 v7, v6, v4
	v_cndmask_b32_e32 v6, v6, v7, vcc
	v_add_u32_e32 v7, 1, v3
	v_cmp_ge_u32_e32 vcc, v6, v4
	s_nop 1
	v_cndmask_b32_e32 v3, v3, v7, vcc
	v_mul_lo_u32 v6, v4, v3
	v_add_u32_e32 v4, v6, v4
	v_cmp_ne_u32_e32 vcc, v5, v4
	s_and_saveexec_b64 s[8:9], vcc
	s_xor_b64 s[8:9], exec, s[8:9]
	s_cbranch_execz .LBB0_1476
	s_waitcnt lgkmcnt(0)
	s_add_u32 s14, s84, 0x33400
	s_addc_u32 s15, s85, 0
	v_add_u32_e32 v3, 1, v3
	v_mul_lo_u32 v3, v3, v2
	v_mov_b32_e32 v2, 0
	global_load_dword v2, v2, s[14:15] sc1
	s_waitcnt vmcnt(0)
	v_cmp_lt_u32_e32 vcc, v2, v3
	s_and_saveexec_b64 s[10:11], vcc
	s_cbranch_execz .LBB0_1475
	s_add_u32 s12, s84, 0x30200
	s_addc_u32 s13, s85, 0
	s_mov_b32 s26, 1
	s_mov_b64 s[16:17], 0
	v_mov_b32_e32 v2, 0
	s_branch .LBB0_1466

; __device__ __forceinline__ unsigned xb_ld(unsigned* p)              { return __hip_atomic_load(p, __ATOMIC_RELAXED, __HIP_MEMORY_SCOPE_AGENT); }
; __device__ __forceinline__ unsigned xb_add(unsigned* p, unsigned v) { return __hip_atomic_fetch_add(p, v, __ATOMIC_RELAXED, __HIP_MEMORY_SCOPE_AGENT); }
; #define XB_SPIN(cond, bar) do { unsigned _sp = 0; while (cond) { __builtin_amdgcn_s_sleep(1); \
;     if ((++_sp & 255u) == 0u) { if (xb_ld(&(bar)[XB_TMO])) break; if (_sp > XB_SPIN_CAP) { atomicAdd(&(bar)[XB_TMO], 1u); break; } } } } while (0)
; __device__ __forceinline__ void xcd_barrier(const XcdBarrier& b) {
;     ...
;             asm volatile("s_waitcnt vmcnt(0)" ::: "memory");
;             const unsigned og = xb_add(&bar[XB_TOP], 1u);
;             const unsigned tg = og / nx;
;             if (og + 1u == (tg + 1u) * nx) xb_add(&bar[XB_TOPGEN], 1u);
;             else XB_SPIN(xb_ld(&bar[XB_TOPGEN]) == tg, bar);
;             __builtin_amdgcn_fence(__ATOMIC_ACQUIRE, "agent");
.LBB0_1479:
	s_or_b64 exec, exec, s[10:11]
	v_cvt_f32_u32_e32 v5, v2
	s_waitcnt vmcnt(0)
	v_readfirstlane_b32 s8, v4
	s_add_u32 s10, s84, 0x33500
	s_addc_u32 s11, s85, 0
	v_rcp_iflag_f32_e32 v5, v5
	v_add_u32_e32 v3, s8, v3
	v_add_u32_e32 v6, 1, v3
	s_mov_b64 s[12:13], 0
	v_mul_f32_e32 v4, 0x4f7ffffe, v5
	v_cvt_u32_f32_e32 v4, v4
	v_sub_u32_e32 v5, 0, v2
	v_mul_lo_u32 v5, v5, v4
	v_mul_hi_u32 v5, v4, v5
	v_add_u32_e32 v4, v4, v5
	v_mul_hi_u32 v4, v3, v4
	v_mul_lo_u32 v5, v4, v2
	v_sub_u32_e32 v3, v3, v5
	v_add_u32_e32 v7, 1, v4
	v_cmp_ge_u32_e32 vcc, v3, v2
	v_sub_u32_e32 v5, v3, v2
	s_nop 0
	v_cndmask_b32_e32 v4, v4, v7, vcc
	v_cndmask_b32_e32 v3, v3, v5, vcc
	v_add_u32_e32 v5, 1, v4
	v_cmp_ge_u32_e32 vcc, v3, v2
	s_nop 1
	v_cndmask_b32_e32 v4, v4, v5, vcc
	v_mul_lo_u32 v3, v2, v4
	v_add_u32_e32 v2, v3, v2
	v_mov_b32_e32 v8, v2
	v_cmp_ne_u32_e32 vcc, v6, v2
	v_mov_b64_e32 v[2:3], s[10:11]
	s_and_saveexec_b64 s[8:9], vcc
	s_cbranch_execz .LBB0_1491
	s_add_u32 s100, s84, 0x33400
	s_addc_u32 s101, s85, 0
	v_mov_b32_e32 v2, 0
	global_load_dword v3, v2, s[100:101] sc1
	s_mov_b64 s[16:17], 0
	s_waitcnt vmcnt(0)
	v_cmp_lt_u32_e32 vcc, v3, v8
	s_and_saveexec_b64 s[14:15], vcc
	s_cbranch_execz .LBB0_1490
	s_add_u32 s12, s84, 0x30200
	s_addc_u32 s13, s85, 0
	s_mov_b32 s26, 1
	s_branch .LBB0_1483

; __device__ __forceinline__ unsigned xb_add(unsigned* p, unsigned v) { return __hip_atomic_fetch_add(p, v, __ATOMIC_RELAXED, __HIP_MEMORY_SCOPE_AGENT); }
; __device__ __forceinline__ void xcd_barrier(const XcdBarrier& b) {
;     ...
;             __builtin_amdgcn_fence(__ATOMIC_ACQUIRE, "agent");
;             xb_add(&bar[XB_XGEN(b.x)], 1u);
;             asm volatile("s_waitcnt vmcnt(0)" ::: "memory");
.LBB0_1493:
	s_or_b64 exec, exec, s[8:9]
	v_mov_b32_e32 v2, 0x2000
	v_mov_b32_e32 v3, 1
	s_waitcnt vmcnt(0)
	s_waitcnt vmcnt(0)
	s_branch .LBB0_1494

; __device__ __forceinline__ unsigned xb_ld(unsigned* p)              { return __hip_atomic_load(p, __ATOMIC_RELAXED, __HIP_MEMORY_SCOPE_AGENT); }
; __device__ __forceinline__ unsigned xb_add(unsigned* p, unsigned v) { return __hip_atomic_fetch_add(p, v, __ATOMIC_RELAXED, __HIP_MEMORY_SCOPE_AGENT); }
; #define XB_SPIN(cond, bar) do { unsigned _sp = 0; while (cond) { __builtin_amdgcn_s_sleep(1); \
;     if ((++_sp & 255u) == 0u) { if (xb_ld(&(bar)[XB_TMO])) break; if (_sp > XB_SPIN_CAP) { atomicAdd(&(bar)[XB_TMO], 1u); break; } } } } while (0)
; __device__ __forceinline__ void xcd_barrier(const XcdBarrier& b) {
;     ...
;         const unsigned old = xb_add(&bar[XB_XSUB(b.x)], 1u);
;         const unsigned gen = old / nloc;
;         if (old + 1u == (gen + 1u) * nloc) {
;             __builtin_amdgcn_fence(__ATOMIC_RELEASE, "agent");
;             asm volatile("s_waitcnt vmcnt(0)" ::: "memory");
;             const unsigned og = xb_add(&bar[XB_TOP], 1u);
;             const unsigned tg = og / nx;
;             if (og + 1u == (tg + 1u) * nx) xb_add(&bar[XB_TOPGEN], 1u);
;             else XB_SPIN(xb_ld(&bar[XB_TOPGEN]) == tg, bar);
;             __builtin_amdgcn_fence(__ATOMIC_ACQUIRE, "agent");
;             xb_add(&bar[XB_XGEN(b.x)], 1u);
;             asm volatile("s_waitcnt vmcnt(0)" ::: "memory");
;         } else {
;             XB_SPIN(xb_ld(&bar[XB_XGEN(b.x)]) == gen, bar);
.LBB0_1963:
	v_readlane_b32 s2, v254, 16
	s_lshl_b32 s2, s2, 8
	v_readlane_b32 s4, v254, 12
	v_readlane_b32 s5, v254, 13
	s_add_u32 s2, s4, s2
	s_addc_u32 s3, s5, 0
	v_mov_b32_e32 v3, 0x1000
	v_mov_b32_e32 v5, 1
	global_atomic_add v5, v3, v5, s[2:3] offset:1024 sc0
	v_cvt_f32_u32_e32 v3, v4
	v_sub_u32_e32 v6, 0, v4
	v_rcp_iflag_f32_e32 v3, v3
	s_nop 0
	v_mul_f32_e32 v3, 0x4f7ffffe, v3
	v_cvt_u32_f32_e32 v3, v3
	v_mul_lo_u32 v6, v6, v3
	v_mul_hi_u32 v6, v3, v6
	v_add_u32_e32 v3, v3, v6
	s_waitcnt vmcnt(0)
	v_mul_hi_u32 v3, v5, v3
	v_mul_lo_u32 v6, v3, v4
	v_sub_u32_e32 v6, v5, v6
	v_add_u32_e32 v7, 1, v3
	v_cmp_ge_u32_e32 vcc, v6, v4
	v_add_u32_e32 v5, 1, v5
	s_nop 0
	v_cndmask_b32_e32 v3, v3, v7, vcc
	v_sub_u32_e32 v7, v6, v4
	v_cndmask_b32_e32 v6, v6, v7, vcc
	v_add_u32_e32 v7, 1, v3
	v_cmp_ge_u32_e32 vcc, v6, v4
	s_nop 1
	v_cndmask_b32_e32 v3, v3, v7, vcc
	v_mul_lo_u32 v6, v4, v3
	v_add_u32_e32 v4, v6, v4
	v_cmp_ne_u32_e32 vcc, v5, v4
	s_and_saveexec_b64 s[4:5], vcc
	s_xor_b64 s[4:5], exec, s[4:5]
	s_cbranch_execz .LBB0_1977
	s_waitcnt lgkmcnt(0)
	s_add_u32 s10, s84, 0x33400
	s_addc_u32 s11, s85, 0
	v_add_u32_e32 v3, 1, v3
	v_mul_lo_u32 v3, v3, v2
	v_mov_b32_e32 v2, 0
	global_load_dword v2, v2, s[10:11] sc1
	s_waitcnt vmcnt(0)
	v_cmp_lt_u32_e32 vcc, v2, v3
	s_and_saveexec_b64 s[6:7], vcc
	s_cbranch_execz .LBB0_1976
	s_add_u32 s8, s84, 0x30200
	s_addc_u32 s9, s85, 0
	s_mov_b32 s22, 1
	s_mov_b64 s[12:13], 0
	v_mov_b32_e32 v2, 0
	s_branch .LBB0_1967

; __device__ __forceinline__ unsigned xb_ld(unsigned* p)              { return __hip_atomic_load(p, __ATOMIC_RELAXED, __HIP_MEMORY_SCOPE_AGENT); }
; #define XB_SPIN(cond, bar) do { unsigned _sp = 0; while (cond) { __builtin_amdgcn_s_sleep(1); \
;     if ((++_sp & 255u) == 0u) { if (xb_ld(&(bar)[XB_TMO])) break; if (_sp > XB_SPIN_CAP) { atomicAdd(&(bar)[XB_TMO], 1u); break; } } } } while (0)
; __device__ __forceinline__ void xcd_barrier(const XcdBarrier& b) {
;     ...
;             else XB_SPIN(xb_ld(&bar[XB_TOPGEN]) == tg, bar);
.LBB0_1969:
	global_load_dword v4, v2, s[10:11] sc1
	s_add_i32 s22, s22, 1
	s_mov_b64 s[18:19], -1
	s_waitcnt vmcnt(0)
	v_cmp_ge_u32_e32 vcc, v4, v3
	s_orn2_b64 s[16:17], vcc, exec
	s_branch .LBB0_1966

; __device__ __forceinline__ unsigned xb_ld(unsigned* p)              { return __hip_atomic_load(p, __ATOMIC_RELAXED, __HIP_MEMORY_SCOPE_AGENT); }
; __device__ __forceinline__ unsigned xb_add(unsigned* p, unsigned v) { return __hip_atomic_fetch_add(p, v, __ATOMIC_RELAXED, __HIP_MEMORY_SCOPE_AGENT); }
; #define XB_SPIN(cond, bar) do { unsigned _sp = 0; while (cond) { __builtin_amdgcn_s_sleep(1); \
;     if ((++_sp & 255u) == 0u) { if (xb_ld(&(bar)[XB_TMO])) break; if (_sp > XB_SPIN_CAP) { atomicAdd(&(bar)[XB_TMO], 1u); break; } } } } while (0)
; __device__ __forceinline__ void xcd_barrier(const XcdBarrier& b) {
;     ...
;             asm volatile("s_waitcnt vmcnt(0)" ::: "memory");
;             const unsigned og = xb_add(&bar[XB_TOP], 1u);
;             const unsigned tg = og / nx;
;             if (og + 1u == (tg + 1u) * nx) xb_add(&bar[XB_TOPGEN], 1u);
;             else XB_SPIN(xb_ld(&bar[XB_TOPGEN]) == tg, bar);
;             __builtin_amdgcn_fence(__ATOMIC_ACQUIRE, "agent");
.LBB0_1980:
	s_or_b64 exec, exec, s[6:7]
	v_cvt_f32_u32_e32 v5, v2
	s_waitcnt vmcnt(0)
	v_readfirstlane_b32 s4, v4
	s_add_u32 s6, s84, 0x33500
	s_addc_u32 s7, s85, 0
	v_rcp_iflag_f32_e32 v5, v5
	v_add_u32_e32 v3, s4, v3
	v_add_u32_e32 v6, 1, v3
	s_mov_b64 s[8:9], 0
	v_mul_f32_e32 v4, 0x4f7ffffe, v5
	v_cvt_u32_f32_e32 v4, v4
	v_sub_u32_e32 v5, 0, v2
	v_mul_lo_u32 v5, v5, v4
	v_mul_hi_u32 v5, v4, v5
	v_add_u32_e32 v4, v4, v5
	v_mul_hi_u32 v4, v3, v4
	v_mul_lo_u32 v5, v4, v2
	v_sub_u32_e32 v3, v3, v5
	v_add_u32_e32 v7, 1, v4
	v_cmp_ge_u32_e32 vcc, v3, v2
	v_sub_u32_e32 v5, v3, v2
	s_nop 0
	v_cndmask_b32_e32 v4, v4, v7, vcc
	v_cndmask_b32_e32 v3, v3, v5, vcc
	v_add_u32_e32 v5, 1, v4
	v_cmp_ge_u32_e32 vcc, v3, v2
	s_nop 1
	v_cndmask_b32_e32 v4, v4, v5, vcc
	v_mul_lo_u32 v3, v2, v4
	v_add_u32_e32 v2, v3, v2
	v_mov_b32_e32 v8, v2
	v_cmp_ne_u32_e32 vcc, v6, v2
	v_mov_b64_e32 v[2:3], s[6:7]
	s_and_saveexec_b64 s[4:5], vcc
	s_cbranch_execz .LBB0_1992
	s_add_u32 s100, s84, 0x33400
	s_addc_u32 s101, s85, 0
	v_mov_b32_e32 v2, 0
	global_load_dword v3, v2, s[100:101] sc1
	s_mov_b64 s[12:13], 0
	s_waitcnt vmcnt(0)
	v_cmp_lt_u32_e32 vcc, v3, v8
	s_and_saveexec_b64 s[10:11], vcc
	s_cbranch_execz .LBB0_1991
	s_add_u32 s8, s84, 0x30200
	s_addc_u32 s9, s85, 0
	s_mov_b32 s22, 1
	s_branch .LBB0_1984

; __device__ __forceinline__ unsigned xb_ld(unsigned* p)              { return __hip_atomic_load(p, __ATOMIC_RELAXED, __HIP_MEMORY_SCOPE_AGENT); }
; #define XB_SPIN(cond, bar) do { unsigned _sp = 0; while (cond) { __builtin_amdgcn_s_sleep(1); \
;     if ((++_sp & 255u) == 0u) { if (xb_ld(&(bar)[XB_TMO])) break; if (_sp > XB_SPIN_CAP) { atomicAdd(&(bar)[XB_TMO], 1u); break; } } } } while (0)
; __device__ __forceinline__ void xcd_barrier(const XcdBarrier& b) {
;     ...
;             else XB_SPIN(xb_ld(&bar[XB_TOPGEN]) == tg, bar);
.LBB0_1986:
	global_load_dword v3, v2, s[100:101] sc1
	s_add_i32 s22, s22, 1
	s_mov_b64 s[16:17], -1
	s_waitcnt vmcnt(0)
	v_cmp_ge_u32_e32 vcc, v3, v8
	s_orn2_b64 s[20:21], vcc, exec
	s_branch .LBB0_1983

; __device__ __forceinline__ unsigned xb_add(unsigned* p, unsigned v) { return __hip_atomic_fetch_add(p, v, __ATOMIC_RELAXED, __HIP_MEMORY_SCOPE_AGENT); }
; __device__ __forceinline__ void xcd_barrier(const XcdBarrier& b) {
;     ...
;             __builtin_amdgcn_fence(__ATOMIC_ACQUIRE, "agent");
;             xb_add(&bar[XB_XGEN(b.x)], 1u);
;             asm volatile("s_waitcnt vmcnt(0)" ::: "memory");
.LBB0_1994:
	s_or_b64 exec, exec, s[4:5]
	v_mov_b32_e32 v2, 0x2000
	v_mov_b32_e32 v3, 1
	s_waitcnt vmcnt(0)
	s_waitcnt vmcnt(0)
	s_branch .LBB0_1995
